# LRU: non-temporal (nt) hint on the write-once flush stores (forward states, y) so they do not displace the shared xa rows in L2
# baseline (speedup 1.0000x reference)
; #define LAS __attribute__((address_space(3)))
; template <int dir>
; __device__ __forceinline__ void lru_pass(LAS unsigned char* lds, const Params& P, int b, int h, int q, bool dry) {
;     ...
;         } else if (!dry) {
; #pragma unroll
;             for (int i = 0; i < 2; ++i) { const int id = tid + i * NTHREADS; *(u32x4*)(Z + ZSLAB(8 + h, (size_t)b * SEQ + t0_prev + (id >> 2)) + q * 32 + (id & 3) * 8) = *(const LAS u32x4*)(TOUT + (id >> 2) * IO_NP + (id & 3) * 16); }
;         }
; __global__ void __launch_bounds__(NTHREADS, 2) fwd_megakernel(Params P) {
;     ...
;         for (int s2 = bx; s2 < 256; s2 += G) { lru_strip(lds, P, ((s2 & 7) << 5) | (s2 >> 3), false); __syncthreads(); }
.Lpp_b_noy:
	s_ashr_i32 s1, s29, 31
	s_add_u32 s0, s26, s29
	s_waitcnt lgkmcnt(0)
	s_barrier
	s_addc_u32 s1, s27, s1
	v_add_u32_e32 v0, v158, v164
	ds_read_b128 v[0:3], v0
	v_lshl_add_u64 v[4:5], s[0:1], 0, v[140:141]
	v_lshlrev_b64 v[4:5], 8, v[4:5]
	v_lshl_add_u64 v[8:9], v[136:137], 0, v[4:5]
	v_add_u32_e32 v4, v158, v152
	ds_read_b128 v[4:7], v4
	s_waitcnt lgkmcnt(1)
	global_store_dwordx4 v[8:9], v[0:3], off nt
	s_add_i32 s2, s2, s34
	s_cmpk_lt_i32 s2, 0x100
	v_lshl_add_u64 v[0:1], s[0:1], 0, v[138:139]
	v_lshlrev_b64 v[0:1], 8, v[0:1]
	v_lshl_add_u64 v[0:1], v[136:137], 0, v[0:1]
	v_mov_b32_e32 v200, 0x3ecc95a3
	v_mov_b32_e32 v201, 0x7f800000
	v_mov_b32_e32 v202, 0x7fc00000
	v_mov_b32_e32 v203, v156
	s_waitcnt lgkmcnt(0)
	global_store_dwordx4 v[0:1], v[4:7], off nt
	s_barrier
	s_barrier
	s_cbranch_scc0 .LBB0_317

; #define LAS __attribute__((address_space(3)))
; template <int dir>
; __device__ __forceinline__ void lru_pass(LAS unsigned char* lds, const Params& P, int b, int h, int q, bool dry) {
;     ...
;             if (sc >= 2) {
;                 if (dir == 0) {
; #pragma unroll
;                     for (int i = 0; i < 4; ++i) { const int id = tid + i * NTHREADS; *(u32x4*)(Hg + (size_t)(t0_prev + (id >> 3)) * DM + (id & 7) * 4) = *(const LAS u32x4*)(TOUT + (id >> 3) * IO_WP + (id & 7) * 16); }
.LBB0_295:
	s_waitcnt lgkmcnt(0)
	s_barrier
	s_setprio 0
	s_cmp_lt_u32 s93, 2
	s_cbranch_scc1 .LBB0_297
	v_add_u32_e32 v48, v129, v149
	ds_read_b128 v[32:35], v48
	v_add_u32_e32 v48, v129, v146
	ds_read_b128 v[36:39], v48
	v_add_u32_e32 v48, v129, v144
	ds_read_b128 v[40:43], v48
	v_add_u32_e32 v48, v129, v142
	ds_read_b128 v[44:47], v48
	v_add_u32_e32 v48, s91, v148
	v_ashrrev_i32_e32 v49, 31, v48
	v_lshlrev_b64 v[48:49], 12, v[48:49]
	v_lshl_add_u64 v[48:49], v[130:131], 0, v[48:49]
	v_add_u32_e32 v50, s91, v145
	v_ashrrev_i32_e32 v51, 31, v50
	v_lshlrev_b64 v[50:51], 12, v[50:51]
	v_lshl_add_u64 v[50:51], v[130:131], 0, v[50:51]
	v_add_u32_e32 v52, s91, v143
	v_ashrrev_i32_e32 v53, 31, v52
	v_lshlrev_b64 v[52:53], 12, v[52:53]
	v_lshl_add_u64 v[52:53], v[130:131], 0, v[52:53]
	v_add_u32_e32 v54, s91, v141
	v_ashrrev_i32_e32 v55, 31, v54
	v_lshlrev_b64 v[54:55], 12, v[54:55]
	v_lshl_add_u64 v[54:55], v[130:131], 0, v[54:55]
	s_waitcnt lgkmcnt(3)
	global_store_dwordx4 v[48:49], v[32:35], off nt
	s_waitcnt lgkmcnt(2)
	global_store_dwordx4 v[50:51], v[36:39], off nt
	s_waitcnt lgkmcnt(1)
	global_store_dwordx4 v[52:53], v[40:43], off nt
	s_waitcnt lgkmcnt(0)
	global_store_dwordx4 v[54:55], v[44:47], off nt

; #define LAS __attribute__((address_space(3)))
; __device__ __forceinline__ int opaque_tid() { int t = threadIdx.x; asm volatile("" : "+v"(t)); return t; }
; template <int dir>
; __device__ __forceinline__ void lru_pass(LAS unsigned char* lds, const Params& P, int b, int h, int q, bool dry) {
;     const int tid = opaque_tid(), lane = tid & 63, wid = __builtin_amdgcn_readfirstlane(tid >> 6), g = lane >> 5, nl = lane & 31;
;     const int chl = q * 32 + nl, ch = h * 128 + chl;
;     LAS unsigned char* XC = lds;
;     LAS float* AGG = (LAS float*)(lds + 256 * XC_PITCH);
;     LAS unsigned char* WB = lds + 256 * XC_PITCH + 2048;
;     LAS float* CWL = (LAS float*)(lds + 256 * XC_PITCH + 2048 + 64 * XC_PITCH);
;     LAS unsigned char* TIN = lds + LRU_IO_OFF;
;     LAS unsigned char* TOUT = lds + LRU_IO_OFF + 256 * (dir == 0 ? IO_NP : IO_WP);
;     bf16_t* Z = (bf16_t*)(P.ws + WS_Z); const bf16_t* ZC = (const bf16_t*)(P.ws + WS_ZC); unsigned* HFW = (unsigned*)(P.ws + WS_HF);
;     const bf16_t* LruW = (const bf16_t*)(P.ws + WS_LRUW);
;     const int cgp = tid & 15, tr = tid >> 4;
;     const int s_i = 16 * ((nl >> 2) & 1) + ((nl >> 3) << 2) + (nl & 3);
;     const bf16_t* Zg = Z + ZSLAB(8 + h, (size_t)b * SEQ) + q * 32;
;     unsigned* Hg = HFW + (size_t)b * SEQ * DM + h * 128 + q * 32;
;     {
; #pragma unroll
;         for (int i = 0; i < 2; ++i) { const int idx = tid + i * NTHREADS, gate = idx >> 9, n = (idx >> 4) & 31, kc = idx & 15;
;             *(LAS u32x4*)(WB + (gate * 32 + n) * XC_PITCH + kc * 16) = *(const u32x4*)(LruW + ((size_t)((dir * 2 + gate) * 8 + h) * 128 + q * 32 + n) * 128 + kc * 8); }
;         const float br = -LOG2E * P.lru_ba[(dir * 8 + h) * 128 + chl], bi = -LOG2E * P.lru_bx[(dir * 8 + h) * 128 + chl];
;         const float lam = P.lru_lambda[dir * 1024 + ch];
;         const float cl = -8.0f * LOG2E * log1pf(__expf(-lam));
;         float carry = 0.f;
;         LruTile cur = lru_tile(Z, ZC, b, h, dir, 0);
;         u32x4 rows[11];
;         constexpr int NIN = dir == 0 ? 2 : 4;
;         u32x4 inr[NIN];
;         lru_load_rows(rows, cur, tr, cgp);
;     ...
;         if (dir == 0) {
; #pragma unroll
;             for (int i = 0; i < 4; ++i) { const int id = tid + i * NTHREADS; *(u32x4*)(Hg + (size_t)(t0_prev + (id >> 3)) * DM + (id & 7) * 4) = *(const LAS u32x4*)(TOUT + (id >> 3) * IO_WP + (id & 7) * 16); }
.Lpp_f_noy:
	s_waitcnt lgkmcnt(0)
	s_barrier
	v_add_u32_e32 v0, v129, v149
	ds_read_b128 v[0:3], v0
	v_add_u32_e32 v4, s97, v148
	v_ashrrev_i32_e32 v5, 31, v4
	v_lshlrev_b64 v[4:5], 12, v[4:5]
	v_lshl_add_u64 v[8:9], v[130:131], 0, v[4:5]
	v_add_u32_e32 v4, v129, v146
	ds_read_b128 v[4:7], v4
	s_waitcnt lgkmcnt(1)
	global_store_dwordx4 v[8:9], v[0:3], off nt
	v_cmp_gt_i32_e32 vcc, 64, v128
	s_nop 0
	v_add_u32_e32 v0, s97, v145
	v_ashrrev_i32_e32 v1, 31, v0
	v_lshlrev_b64 v[0:1], 12, v[0:1]
	v_lshl_add_u64 v[0:1], v[130:131], 0, v[0:1]
	s_waitcnt lgkmcnt(0)
	global_store_dwordx4 v[0:1], v[4:7], off nt
	v_add_u32_e32 v0, v129, v144
	ds_read_b128 v[0:3], v0
	v_add_u32_e32 v4, s97, v143
	v_ashrrev_i32_e32 v5, 31, v4
	v_lshlrev_b64 v[4:5], 12, v[4:5]
	v_lshl_add_u64 v[8:9], v[130:131], 0, v[4:5]
	v_add_u32_e32 v4, v129, v142
	ds_read_b128 v[4:7], v4
	s_waitcnt lgkmcnt(1)
	global_store_dwordx4 v[8:9], v[0:3], off nt
	s_nop 1
	v_add_u32_e32 v0, s97, v141
	v_ashrrev_i32_e32 v1, 31, v0
	v_lshlrev_b64 v[0:1], 12, v[0:1]
	v_lshl_add_u64 v[0:1], v[130:131], 0, v[0:1]
	s_waitcnt lgkmcnt(0)
	global_store_dwordx4 v[0:1], v[4:7], off nt
	s_waitcnt lgkmcnt(0)
	v_mov_b32_e32 v32, v167
	s_barrier
	s_or_b32 s0, s26, 16
	v_and_b32_e32 v15, 31, v32
	v_or_b32_e32 v17, s28, v15
	v_add_u32_e32 v13, 0x200, v32
	v_or_b32_e32 v8, s27, v17
	v_ashrrev_i32_e32 v11, 9, v32
	v_ashrrev_i32_e32 v14, 9, v13
	v_lshlrev_b32_e32 v8, 2, v8
	v_mov_b32_e32 v9, v65
	v_lshl_add_u32 v2, v11, 3, s0
	v_lshl_add_u32 v6, v14, 3, s0
	v_lshl_add_u64 v[8:9], s[64:65], 0, v[8:9]
	s_movk_i32 s0, 0x1000
	v_add_co_u32_e32 v8, vcc, s0, v8
	v_and_b32_e32 v12, 15, v32
	s_nop 0
	v_addc_co_u32_e32 v9, vcc, 0, v9, vcc
	global_load_dword v16, v[8:9], off
	v_bfe_u32 v10, v32, 4, 5
	v_lshlrev_b32_e32 v64, 4, v12
	v_ashrrev_i32_e32 v3, 31, v2
	v_ashrrev_i32_e32 v7, 31, v6
	v_or_b32_e32 v4, s28, v10
	v_lshl_add_u64 v[0:1], s[38:39], 0, v[64:65]
	v_lshlrev_b64 v[2:3], 15, v[2:3]
	v_lshlrev_b64 v[6:7], 15, v[6:7]
	v_lshlrev_b32_e32 v4, 8, v4
	v_mov_b32_e32 v5, v65
	v_lshl_add_u64 v[2:3], v[0:1], 0, v[2:3]
	v_lshl_add_u64 v[0:1], v[0:1], 0, v[6:7]
	v_lshl_add_u64 v[2:3], v[2:3], 0, v[4:5]
	v_lshl_add_u64 v[4:5], v[0:1], 0, v[4:5]
	global_load_dwordx4 v[0:3], v[2:3], off
	s_nop 0
	global_load_dwordx4 v[4:7], v[4:5], off
	v_lshrrev_b32_e32 v8, 1, v32
	v_lshlrev_b32_e32 v9, 2, v32
	v_and_b32_e32 v20, 12, v8
	v_lshl_or_b32 v11, v11, 5, v10
	v_add_u32_e32 v8, s88, v64
	v_lshl_or_b32 v14, v14, 5, v10
	v_mad_u64_u32 v[10:11], s[6:7], v11, s89, v[8:9]
	s_or_b32 s8, s26, 8
	v_and_or_b32 v20, v9, 16, v20
	v_lshlrev_b32_e32 v21, 2, v17
	v_mad_u64_u32 v[8:9], s[6:7], v14, s89, v[8:9]
	v_lshl_or_b32 v9, s8, 9, v21
	global_load_dword v14, v9, s[58:59]
	s_nop 0
	global_load_dword v9, v9, s[62:63]
	s_mov_b32 s80, 0x3f2aaaab
	s_mov_b32 s81, 0x3f317218
	s_mov_b32 s91, 0x7f800000
	s_mov_b32 s92, 0x33800000
	v_ashrrev_i32_e32 v33, 4, v32
	v_lshlrev_b32_e32 v34, 3, v12
	v_readfirstlane_b32 s4, v32
	s_lshl_b64 s[0:1], s[78:79], 11
	s_lshl_b32 s5, s8, 14
	s_ashr_i32 s6, s4, 6
	s_add_u32 s26, s0, s5
	s_addc_u32 s27, s1, 0
	s_lshl_b32 s0, s28, 1
	v_readlane_b32 s1, v255, 10
	v_and_b32_e32 v19, 3, v32
	s_add_u32 s0, s1, s0
	v_bfe_u32 v18, v32, 5, 1
	v_add_u32_e32 v44, 0, v64
	v_lshlrev_b32_e32 v64, 4, v19
	s_addc_u32 s1, s3, 0
	v_lshl_add_u64 v[136:137], s[0:1], 0, v[64:65]
	s_lshl_b32 s0, s6, 5
	v_lshlrev_b32_e32 v46, 4, v18
	v_or_b32_e32 v37, s0, v46
	v_add_u32_e32 v158, s86, v64
	v_or_b32_e32 v64, 4, v37
	s_movk_i32 s93, 0x880
	v_ashrrev_i32_e32 v36, 3, v32
	v_ashrrev_i32_e32 v38, 3, v13
	v_ashrrev_i32_e32 v140, 2, v32
	v_sub_u32_e32 v39, 0xff, v37
	v_sub_u32_e32 v64, 0xff, v64
	v_lshl_add_u32 v160, v33, 3, -1
	v_mul_lo_u32 v52, v33, s93
	v_lshl_or_b32 v110, v33, 13, v34
	v_mov_b32_e32 v111, v65
	v_lshlrev_b64 v[110:111], 1, v[110:111]
	v_lshl_add_u64 v[108:109], s[48:49], 0, v[110:111]
	global_load_dwordx4 v[68:71], v[108:109], off offset:-2048
	global_load_dwordx4 v[72:75], v[108:109], off
	global_load_dwordx4 v[76:79], v[108:109], off offset:2048
	v_lshl_add_u64 v[108:109], s[50:51], 0, v[110:111]
	global_load_dwordx4 v[80:83], v[108:109], off
	v_lshl_add_u64 v[108:109], s[56:57], 0, v[110:111]
	global_load_dwordx4 v[84:87], v[108:109], off
	v_lshl_add_u64 v[108:109], s[60:61], 0, v[110:111]
	global_load_dwordx4 v[88:91], v[108:109], off
	v_lshl_add_u64 v[108:109], s[66:67], 0, v[110:111]
	global_load_dwordx4 v[92:95], v[108:109], off
	v_lshl_add_u64 v[108:109], s[70:71], 0, v[110:111]
	global_load_dwordx4 v[96:99], v[108:109], off
	v_lshl_add_u64 v[108:109], s[72:73], 0, v[110:111]
	global_load_dwordx4 v[100:103], v[108:109], off
	v_lshl_add_u64 v[108:109], s[74:75], 0, v[110:111]
	global_load_dwordx4 v[104:107], v[108:109], off
	v_lshl_add_u64 v[108:109], s[76:77], 0, v[110:111]
	global_load_dwordx4 v[108:111], v[108:109], off
	s_waitcnt vmcnt(14)
	ds_write_b128 v10, v[0:3]
	s_waitcnt vmcnt(13)
; template <int dir>
; __device__ __forceinline__ void lru_pass(LAS unsigned char* lds, const Params& P, int b, int h, int q, bool dry) {
;     ...
;         const float br = -LOG2E * P.lru_ba[(dir * 8 + h) * 128 + chl], bi = -LOG2E * P.lru_bx[(dir * 8 + h) * 128 + chl];
;         const float lam = P.lru_lambda[dir * 1024 + ch];
;         const float cl = -8.0f * LOG2E * log1pf(__expf(-lam));
;         float carry = 0.f;
;         LruTile cur = lru_tile(Z, ZC, b, h, dir, 0);
;         u32x4 rows[11];
;         constexpr int NIN = dir == 0 ? 2 : 4;
;         u32x4 inr[NIN];
;         lru_load_rows(rows, cur, tr, cgp);
;     ...
;             const int sbase = 32 * wid + 16 * g;
;             { const int sl = 32 * wid + s_i; const int tlA = dir == 0 ? sl : 255 - sl;
;               const LAS unsigned char* ap = XC + tlA * XC_PITCH + 16 * g;
;               const LAS unsigned char* wrp = WB + nl * XC_PITCH + 16 * g; const LAS unsigned char* wip = wrp + 32 * XC_PITCH;
; #pragma unroll
;               for (int ks = 0; ks < 8; ++ks) { const bf16x8 A = *(const LAS bf16x8*)(ap + 32 * ks);
;                   const bf16x8 Br = *(const LAS bf16x8*)(wrp + 32 * ks), Bi = *(const LAS bf16x8*)(wip + 32 * ks);
;                   zr = __builtin_amdgcn_mfma_f32_32x32x16_bf16(A, Br, zr, 0, 0, 0); zi = __builtin_amdgcn_mfma_f32_32x32x16_bf16(A, Bi, zi, 0, 0, 0); } }
;             unsigned xcb[16], pk[16];
; #pragma unroll
;             for (int v = 0; v < 16; ++v) { const int s = sbase + v; const int tl = dir == 0 ? s : 255 - s; xcb[v] = *(const LAS bf16_t*)(XC + tl * XC_PITCH + chl * 2);
;                 if (dir == 0) pk[v] = *(const LAS bf16_t*)(TIN + tl * IO_NP + nl * 2); else pk[v] = *(const LAS unsigned*)(TIN + tl * IO_WP + nl * 4); }
;             float Pp = 1.f, E = 0.f;
; #pragma unroll
;             for (int v = 0; v < 16; ++v) {
;                 const float xcv = __uint_as_float(xcb[v] << 16);
;                 const float r = __builtin_amdgcn_rcpf(1.0f + __builtin_amdgcn_exp2f(zr[v]));
;                 const float ig = __builtin_amdgcn_rcpf(1.0f + __builtin_amdgcn_exp2f(zi[v]));
;                 const float a = __builtin_amdgcn_exp2f(cl * r);
;                 const float sq = __builtin_amdgcn_sqrtf(fmaf(-a, a, 1.0f));
;                 const float u = sq * ig * xcv;
;                 E = fmaf(a, E, u); Pp *= a; zr[v] = E; zi[v] = Pp; }
	ds_write_b128 v8, v[4:7]
	v_mul_f32_e32 v11, 0xbfb8aa3b, v16
	v_exp_f32_e32 v11, v11
	v_mul_lo_u32 v57, v39, s89
	v_mul_lo_u32 v58, v39, s30
	v_mul_lo_u32 v114, v64, s89
	v_add_f32_e32 v2, 1.0, v11
	v_add_f32_e32 v3, -1.0, v2
	v_frexp_mant_f32_e32 v4, v2
	v_cvt_f64_f32_e32 v[0:1], v2
	v_sub_f32_e32 v5, v3, v2
	v_frexp_exp_i32_f64_e32 v0, v[0:1]
	v_cmp_gt_f32_e32 vcc, s80, v4
	v_sub_f32_e32 v3, v11, v3
	v_add_f32_e32 v1, 1.0, v5
	v_subbrev_co_u32_e32 v0, vcc, 0, v0, vcc
	v_add_f32_e32 v1, v3, v1
	v_sub_u32_e32 v3, 0, v0
	v_ldexp_f32 v2, v2, v3
	v_ldexp_f32 v1, v1, v3
	v_add_f32_e32 v3, -1.0, v2
	v_add_f32_e32 v4, 1.0, v2
	v_add_f32_e32 v5, 1.0, v3
	v_add_f32_e32 v6, -1.0, v4
	v_sub_f32_e32 v5, v2, v5
	v_sub_f32_e32 v2, v2, v6
	v_add_f32_e32 v5, v1, v5
	v_add_f32_e32 v1, v1, v2
	v_add_f32_e32 v7, v4, v1
	v_rcp_f32_e32 v8, v7
	v_add_f32_e32 v2, v3, v5
	v_sub_f32_e32 v4, v7, v4
	v_sub_f32_e32 v3, v2, v3
	v_sub_f32_e32 v1, v1, v4
	v_mul_f32_e32 v4, v2, v8
	v_sub_f32_e32 v3, v5, v3
	v_mul_f32_e32 v5, v7, v4
	v_fma_f32 v10, v4, v7, -v5
	v_fmac_f32_e32 v10, v4, v1
	v_add_f32_e32 v16, v5, v10
	v_sub_f32_e32 v21, v2, v16
	v_sub_f32_e32 v2, v2, v21
	v_sub_f32_e32 v5, v16, v5
	v_sub_f32_e32 v2, v2, v16
	v_sub_f32_e32 v5, v5, v10
	v_add_f32_e32 v2, v3, v2
	v_add_f32_e32 v2, v5, v2
	v_add_f32_e32 v3, v21, v2
	v_mul_f32_e32 v5, v8, v3
	v_sub_f32_e32 v10, v21, v3
	v_mul_f32_e32 v16, v7, v5
	v_add_f32_e32 v2, v2, v10
	v_add_f32_e32 v10, v4, v5
	v_fma_f32 v7, v5, v7, -v16
	v_sub_f32_e32 v4, v10, v4
	v_fmac_f32_e32 v7, v5, v1
	v_sub_f32_e32 v1, v5, v4
	v_add_f32_e32 v4, v16, v7
	v_sub_f32_e32 v5, v4, v16
	v_sub_f32_e32 v16, v3, v4
	v_sub_f32_e32 v3, v3, v16
	v_sub_f32_e32 v3, v3, v4
	v_cvt_f32_i32_e32 v0, v0
	v_sub_f32_e32 v5, v5, v7
	v_add_f32_e32 v2, v2, v3
	v_add_f32_e32 v2, v5, v2
	v_add_f32_e32 v2, v16, v2
	v_mul_f32_e32 v2, v8, v2
	v_mul_f32_e32 v6, 0x3f317218, v0
	v_add_f32_e32 v1, v1, v2
	v_add_f32_e32 v2, v10, v1
	v_fma_f32 v5, v0, s81, -v6
	v_fmac_f32_e32 v5, 0xb102e308, v0
	v_sub_f32_e32 v0, v2, v10
	v_mul_f32_e32 v3, v2, v2
	v_sub_f32_e32 v0, v1, v0
	v_add_f32_e32 v1, v6, v5
	v_fmamk_f32 v4, v3, 0x3e9b6dac, v200
	v_sub_f32_e32 v6, v1, v6
	v_fmaak_f32 v4, v3, v4, 0x3f2aaada
	v_sub_f32_e32 v5, v5, v6
	v_ldexp_f32 v6, v2, 1
	v_mul_f32_e32 v2, v2, v3
	v_mul_f32_e32 v2, v2, v4
	v_add_f32_e32 v3, v6, v2
	v_sub_f32_e32 v4, v3, v6
	v_ldexp_f32 v0, v0, 1
	v_sub_f32_e32 v2, v2, v4
	v_add_f32_e32 v0, v0, v2
	v_add_f32_e32 v2, v3, v0
	v_sub_f32_e32 v3, v2, v3
	v_sub_f32_e32 v0, v0, v3
	v_add_f32_e32 v3, v1, v2
	v_sub_f32_e32 v4, v3, v1
	v_sub_f32_e32 v6, v3, v4
	v_sub_f32_e32 v1, v1, v6
	v_sub_f32_e32 v2, v2, v4
	v_add_f32_e32 v1, v2, v1
	v_add_f32_e32 v2, v5, v0
	v_sub_f32_e32 v4, v2, v5
	v_add_f32_e32 v1, v2, v1
	v_sub_f32_e32 v6, v2, v4
	v_add_f32_e32 v2, v3, v1
	v_sub_f32_e32 v5, v5, v6
	v_sub_f32_e32 v0, v0, v4
	v_sub_f32_e32 v3, v2, v3
	v_add_f32_e32 v0, v0, v5
	v_sub_f32_e32 v1, v1, v3
	v_add_f32_e32 v0, v0, v1
	v_add_f32_e32 v0, v2, v0
	v_cmp_neq_f32_e32 vcc, s91, v11
	v_mov_b32_e32 v1, v65
	v_mul_lo_u32 v115, v64, s30
	v_cndmask_b32_e32 v0, v201, v0, vcc
	v_cmp_ngt_f32_e32 vcc, -1.0, v11
	v_mul_lo_u32 v206, v39, s87
	v_mul_lo_u32 v210, v64, s87
	v_cndmask_b32_e32 v0, v202, v0, vcc
	v_cmp_neq_f32_e32 vcc, -1.0, v11
	v_ashrrev_i32_e32 v39, 31, v38
	v_sub_u32_e32 v41, 0xfe, v37
	v_cndmask_b32_e32 v0, v203, v0, vcc
	v_cmp_lt_f32_e64 vcc, |v11|, s92
	v_mul_lo_u32 v59, v41, s89
	v_mul_lo_u32 v60, v41, s30
	v_cndmask_b32_e32 v6, v0, v11, vcc
	v_lshlrev_b32_e32 v2, 4, v32
	v_and_b32_e32 v2, 0x70, v2
	v_lshlrev_b32_e32 v1, 2, v15
	v_add_u32_e32 v45, s95, v2
	v_or3_b32 v2, v19, v20, s0
	s_and_b32 s0, s4, 0x3fffffc0
	v_add_u32_e32 v161, s94, v1
	s_cmp_eq_u32 s6, 7
	v_lshl_add_u32 v254, s0, 2, v161
	s_cselect_b64 s[0:1], -1, 0
	s_cmp_eq_u32 s6, 6
	s_cselect_b64 s[16:17], -1, 0
	s_cmp_eq_u32 s6, 5
	s_cselect_b64 s[4:5], -1, 0
	s_cmp_eq_u32 s6, 4
	s_cselect_b64 s[8:9], -1, 0
	s_cmp_eq_u32 s6, 3
	s_cselect_b64 s[10:11], -1, 0
	s_cmp_eq_u32 s6, 2
	s_cselect_b64 s[12:13], -1, 0
	s_cmp_eq_u32 s6, 1
	s_cselect_b64 s[14:15], -1, 0
	s_lshl_b32 s6, s25, 7
	s_and_b32 s6, s6, 0xe00
	s_lshl_b32 s7, s29, 7
	s_or_b32 s6, s7, s6
	s_add_u32 s6, s6, s44
	v_add_u32_e32 v50, s95, v1
	v_add_u32_e32 v1, 0x400, v32
	s_addc_u32 s7, 0, s45
	v_ashrrev_i32_e32 v40, 3, v1
	v_add_u32_e32 v1, 0x600, v32
	v_and_b32_e32 v32, 7, v32
	s_add_u32 s18, s84, s46
	v_lshlrev_b32_e32 v64, 4, v32
	v_lshl_or_b32 v32, v33, 10, v34
	v_mov_b32_e32 v33, v65
	s_addc_u32 s19, s85, s47
	v_lshl_add_u64 v[144:145], v[32:33], 1, s[18:19]
	v_lshlrev_b64 v[32:33], 12, v[38:39]
	v_lshl_add_u64 v[32:33], s[6:7], 0, v[32:33]
	v_mul_lo_u32 v207, v41, s87
	v_lshl_add_u64 v[32:33], v[32:33], 0, v[64:65]
	v_ashrrev_i32_e32 v41, 31, v40
	v_or_b32_e32 v43, 2, v37
	v_lshl_add_u64 v[252:253], s[42:43], 0, v[32:33]
	v_lshlrev_b64 v[32:33], 12, v[40:41]
	v_ashrrev_i32_e32 v42, 3, v1
	v_sub_u32_e32 v43, 0xff, v43
	v_or_b32_e32 v63, 3, v37
	v_or_b32_e32 v66, 5, v37
	v_or_b32_e32 v67, 6, v37
	v_or_b32_e32 v120, 7, v37
	v_or_b32_e32 v123, 8, v37
	v_or_b32_e32 v126, 9, v37
	v_or_b32_e32 v129, 10, v37
	v_or_b32_e32 v132, 11, v37
	v_or_b32_e32 v135, 12, v37
	v_or_b32_e32 v142, 13, v37
	v_or_b32_e32 v143, 14, v37
	v_or_b32_e32 v37, 15, v37
	v_lshl_add_u64 v[32:33], s[6:7], 0, v[32:33]
	v_mul_lo_u32 v61, v43, s89
	v_mul_lo_u32 v62, v43, s30
	v_sub_u32_e32 v37, 0xff, v37
	v_mul_lo_u32 v208, v43, s87
	v_lshl_add_u64 v[32:33], v[32:33], 0, v[64:65]
	v_ashrrev_i32_e32 v43, 31, v42
	v_sub_u32_e32 v2, 0xff, v2
	v_mul_lo_u32 v204, v37, s89
	v_mul_lo_u32 v205, v37, s30
	v_mul_lo_u32 v221, v37, s87
	v_ashrrev_i32_e32 v37, 31, v36
	v_lshl_add_u64 v[154:155], s[42:43], 0, v[32:33]
	v_lshlrev_b64 v[32:33], 12, v[42:43]
	v_mul_lo_u32 v2, v2, s89
	v_mul_lo_u32 v53, v36, s30
	v_sub_u32_e32 v63, 0xff, v63
	v_sub_u32_e32 v66, 0xff, v66
	v_sub_u32_e32 v67, 0xff, v67
	v_sub_u32_e32 v120, 0xff, v120
	v_sub_u32_e32 v123, 0xff, v123
	v_sub_u32_e32 v126, 0xff, v126
	v_lshlrev_b64 v[36:37], 12, v[36:37]
	v_lshl_add_u64 v[32:33], s[6:7], 0, v[32:33]
	v_lshlrev_b32_e32 v35, 5, v12
	v_add_u32_e32 v47, 0, v2
	v_mov_b32_e32 v2, s88
	v_lshl_add_u32 v49, v17, 1, 0
	v_lshl_add_u32 v51, v15, 1, s86
	v_mul_lo_u32 v112, v63, s89
	v_mul_lo_u32 v113, v63, s30
	v_mul_lo_u32 v116, v66, s89
	v_mul_lo_u32 v117, v66, s30
	v_mul_lo_u32 v118, v67, s89
	v_mul_lo_u32 v119, v67, s30
	v_mul_lo_u32 v121, v120, s89
	v_mul_lo_u32 v122, v120, s30
	v_mul_lo_u32 v124, v123, s89
	v_mul_lo_u32 v125, v123, s30
	v_mul_lo_u32 v127, v126, s89
	v_mul_lo_u32 v128, v126, s30
	v_sub_u32_e32 v129, 0xff, v129
	v_sub_u32_e32 v132, 0xff, v132
	v_sub_u32_e32 v135, 0xff, v135
	v_sub_u32_e32 v142, 0xff, v142
	v_sub_u32_e32 v143, 0xff, v143
	v_mul_lo_u32 v211, v66, s87
	v_mul_lo_u32 v212, v67, s87
	v_mul_lo_u32 v120, v120, s87
	v_mul_lo_u32 v123, v123, s87
	v_mul_lo_u32 v126, v126, s87
	v_lshl_add_u64 v[36:37], s[6:7], 0, v[36:37]
	v_lshl_add_u64 v[32:33], v[32:33], 0, v[64:65]
	v_mov_b32_e32 v66, v65
	v_mov_b32_e32 v67, v65
	s_waitcnt vmcnt(12)
; #define LAS __attribute__((address_space(3)))
; template <int dir>
; __device__ __forceinline__ void lru_pass(LAS unsigned char* lds, const Params& P, int b, int h, int q, bool dry) {
;     ...
;         const float br = -LOG2E * P.lru_ba[(dir * 8 + h) * 128 + chl], bi = -LOG2E * P.lru_bx[(dir * 8 + h) * 128 + chl];
;         const float lam = P.lru_lambda[dir * 1024 + ch];
;         const float cl = -8.0f * LOG2E * log1pf(__expf(-lam));
;         float carry = 0.f;
;         LruTile cur = lru_tile(Z, ZC, b, h, dir, 0);
;         u32x4 rows[11];
;         constexpr int NIN = dir == 0 ? 2 : 4;
;         u32x4 inr[NIN];
;         lru_load_rows(rows, cur, tr, cgp);
; #pragma unroll
;         for (int i = 0; i < NIN; ++i) inr[i] = (u32x4){0u, 0u, 0u, 0u};
;         int t0_prev = 0;
;         for (int sc = 0; sc < 9; ++sc) {
;             const bool isctx = (sc == 0);
;             const int t0 = cur.t0;
; #pragma unroll
;             for (int j = 0; j < 11; ++j) { if (j != 0 && j < 9) continue;
;                 const int t = t0 + tr * 8 - 1 + j; if (t < 0 || t >= cur.L) rows[j] = (u32x4){0u, 0u, 0u, 0u}; }
;             f32x2 cw2[4][4], cb2[4];
; #pragma unroll
;             for (int k = 0; k < 5; ++k) { const f32x4 a = *(const LAS f32x4*)(CWL + k * 128 + cgp * 8), c2 = *(const LAS f32x4*)(CWL + k * 128 + cgp * 8 + 4);
;                 if (k < 4) { cw2[k][0] = (f32x2){a[0], a[1]}; cw2[k][1] = (f32x2){a[2], a[3]}; cw2[k][2] = (f32x2){c2[0], c2[1]}; cw2[k][3] = (f32x2){c2[2], c2[3]}; }
;                 else { cb2[0] = (f32x2){a[0], a[1]}; cb2[1] = (f32x2){a[2], a[3]}; cb2[2] = (f32x2){c2[0], c2[1]}; cb2[3] = (f32x2){c2[2], c2[3]}; } }
	v_mul_f32_e32 v0, 0xbfb8aa3b, v14
	s_waitcnt vmcnt(11)
	v_mul_f32_e32 v16, 0xbfb8aa3b, v9
	v_mad_u32_u24 v48, v15, s89, v2
	v_mul_lo_u32 v54, v38, s30
	v_mul_lo_u32 v55, v40, s30
	v_mul_lo_u32 v56, v42, s30
	v_ashrrev_i32_e32 v138, 2, v13
	v_mul_lo_u32 v130, v129, s89
	v_mul_lo_u32 v131, v129, s30
	v_mul_lo_u32 v133, v132, s89
	v_mul_lo_u32 v134, v132, s30
	v_mul_lo_u32 v146, v135, s89
	v_mul_lo_u32 v147, v135, s30
	v_mul_lo_u32 v148, v142, s89
	v_mul_lo_u32 v149, v142, s30
	v_mul_lo_u32 v162, v143, s89
	v_mul_lo_u32 v163, v143, s30
	v_mul_lo_u32 v63, v63, s87
	v_mul_lo_u32 v129, v129, s87
	v_mul_lo_u32 v132, v132, s87
	v_mul_lo_u32 v135, v135, s87
	v_mul_lo_u32 v219, v142, s87
	v_mul_lo_u32 v220, v143, s87
	v_lshl_add_u64 v[36:37], v[36:37], 0, v[64:65]
	v_lshl_add_u64 v[150:151], s[42:43], 0, v[32:33]
	v_mov_b32_e32 v64, v65
	v_add_u32_e32 v32, 0, v35
	v_add_u32_e32 v180, v49, v112
	v_add_u32_e32 v181, v50, v113
	v_add_u32_e32 v182, v49, v114
	v_add_u32_e32 v183, v50, v115
	v_add_u32_e32 v184, v49, v116
	v_add_u32_e32 v185, v50, v117
	v_add_u32_e32 v186, v49, v118
	v_add_u32_e32 v187, v50, v119
	v_add_u32_e32 v188, v49, v121
	v_add_u32_e32 v189, v50, v122
	v_add_u32_e32 v190, v49, v124
	v_add_u32_e32 v191, v50, v125
	v_add_u32_e32 v192, v49, v127
	v_add_u32_e32 v213, v51, v120
	v_add_u32_e32 v214, v51, v123
	v_add_u32_e32 v215, v51, v126
	v_mov_b64_e32 v[114:115], v[66:67]
	v_mov_b64_e32 v[118:119], v[66:67]
	v_mov_b64_e32 v[122:123], v[66:67]
	v_mov_b64_e32 v[126:127], v[66:67]
	s_mov_b32 s78, 0
	v_mov_b32_e32 v156, 0xff800000
	v_mul_f32_e32 v159, 0xc138aa3b, v6
	v_cmp_eq_u32_e32 vcc, 0, v18
	v_mul_lo_u32 v164, v140, s87
	v_ashrrev_i32_e32 v141, 31, v140
	v_mul_lo_u32 v152, v138, s87
	v_ashrrev_i32_e32 v139, 31, v138
	v_mov_b32_e32 v1, v0
	v_mov_b32_e32 v2, v0
	v_mov_b32_e32 v3, v0
	v_mov_b32_e32 v4, v0
	v_mov_b32_e32 v5, v0
	v_mov_b32_e32 v6, v0
	v_mov_b32_e32 v7, v0
	v_mov_b32_e32 v8, v0
	v_mov_b32_e32 v9, v0
	v_mov_b32_e32 v10, v0
	v_mov_b32_e32 v11, v0
	v_mov_b32_e32 v12, v0
	v_mov_b32_e32 v13, v0
	v_mov_b32_e32 v14, v0
	v_mov_b32_e32 v15, v0
	v_mov_b32_e32 v17, v16
	v_mov_b32_e32 v18, v16
	v_mov_b32_e32 v19, v16
	v_mov_b32_e32 v20, v16
	v_mov_b32_e32 v21, v16
	v_mov_b32_e32 v22, v16
	v_mov_b32_e32 v23, v16
	v_mov_b32_e32 v24, v16
	v_mov_b32_e32 v25, v16
	v_mov_b32_e32 v26, v16
	v_mov_b32_e32 v27, v16
	v_mov_b32_e32 v28, v16
	v_mov_b32_e32 v29, v16
	v_mov_b32_e32 v30, v16
	v_mov_b32_e32 v31, v16
	v_lshl_add_u64 v[142:143], s[42:43], 0, v[36:37]
	s_movk_i32 s28, 0x100
	v_mov_b32_e32 v222, 0
	s_mov_b64 s[44:45], 0
	s_movk_i32 s25, 0x700
	v_add_u32_e32 v165, 0x15c00, v32
	v_add_u32_e32 v166, v44, v52
	v_add_u32_e32 v168, v45, v53
	v_add_u32_e32 v169, v45, v54
	v_add_u32_e32 v170, v45, v55
	v_add_u32_e32 v171, v45, v56
	v_add_u32_e32 v172, v47, v46
	v_add_u32_e32 v173, v48, v46
	v_add_u32_e32 v174, v49, v57
	v_add_u32_e32 v175, v50, v58
	v_add_u32_e32 v176, v49, v59
	v_add_u32_e32 v177, v50, v60
	v_add_u32_e32 v178, v49, v61
	v_add_u32_e32 v179, v50, v62
	v_add_u32_e32 v193, v50, v128
	v_add_u32_e32 v194, v49, v130
	v_add_u32_e32 v195, v50, v131
	v_add_u32_e32 v196, v49, v133
	v_add_u32_e32 v197, v50, v134
	v_add_u32_e32 v198, v49, v146
	v_add_u32_e32 v199, v50, v147
	v_add_u32_e32 v200, v49, v148
	v_add_u32_e32 v201, v50, v149
	v_add_u32_e32 v202, v49, v162
	v_add_u32_e32 v203, v50, v163
	v_add_u32_e32 v204, v49, v204
	v_add_u32_e32 v205, v50, v205
	v_add_u32_e32 v206, v51, v206
	v_add_u32_e32 v207, v51, v207
	v_add_u32_e32 v208, v51, v208
	v_add_u32_e32 v209, v51, v63
	v_add_u32_e32 v210, v51, v210
	v_add_u32_e32 v211, v51, v211
	v_add_u32_e32 v212, v51, v212
	v_add_u32_e32 v216, v51, v129
	v_add_u32_e32 v217, v51, v132
	v_add_u32_e32 v218, v51, v135
	v_add_u32_e32 v219, v51, v219
	v_add_u32_e32 v220, v51, v220
	v_add_u32_e32 v221, v51, v221
; #define LAS __attribute__((address_space(3)))
; template <int dir>
; __device__ __forceinline__ void lru_pass(LAS unsigned char* lds, const Params& P, int b, int h, int q, bool dry) {
;     ...
;             const int sbase = 32 * wid + 16 * g;
;             { const int sl = 32 * wid + s_i; const int tlA = dir == 0 ? sl : 255 - sl;
;               const LAS unsigned char* ap = XC + tlA * XC_PITCH + 16 * g;
;               const LAS unsigned char* wrp = WB + nl * XC_PITCH + 16 * g; const LAS unsigned char* wip = wrp + 32 * XC_PITCH;
; #pragma unroll
;               for (int ks = 0; ks < 8; ++ks) { const bf16x8 A = *(const LAS bf16x8*)(ap + 32 * ks);
;                   const bf16x8 Br = *(const LAS bf16x8*)(wrp + 32 * ks), Bi = *(const LAS bf16x8*)(wip + 32 * ks);
;                   zr = __builtin_amdgcn_mfma_f32_32x32x16_bf16(A, Br, zr, 0, 0, 0); zi = __builtin_amdgcn_mfma_f32_32x32x16_bf16(A, Bi, zi, 0, 0, 0); } }
;             unsigned xcb[16], pk[16];
; #pragma unroll
;             for (int v = 0; v < 16; ++v) { const int s = sbase + v; const int tl = dir == 0 ? s : 255 - s; xcb[v] = *(const LAS bf16_t*)(XC + tl * XC_PITCH + chl * 2);
;                 if (dir == 0) pk[v] = *(const LAS bf16_t*)(TIN + tl * IO_NP + nl * 2); else pk[v] = *(const LAS unsigned*)(TIN + tl * IO_WP + nl * 4); }
;             float Pp = 1.f, E = 0.f;
; #pragma unroll
;             for (int v = 0; v < 16; ++v) {
;                 const float xcv = __uint_as_float(xcb[v] << 16);
;                 const float r = __builtin_amdgcn_rcpf(1.0f + __builtin_amdgcn_exp2f(zr[v]));
;                 const float ig = __builtin_amdgcn_rcpf(1.0f + __builtin_amdgcn_exp2f(zi[v]));
;                 const float a = __builtin_amdgcn_exp2f(cl * r);
;                 const float sq = __builtin_amdgcn_sqrtf(fmaf(-a, a, 1.0f));
;                 const float u = sq * ig * xcv;
;                 E = fmaf(a, E, u); Pp *= a; zr[v] = E; zi[v] = Pp; }
;             const float Po = __shfl_xor(Pp, 32), Eo = __shfl_xor(E, 32);
;             const float P0 = g ? Po : Pp, E0 = g ? Eo : E, P1 = g ? Pp : Po, E1 = g ? E : Eo;
;             if (g == 0) { AGG[(wid * 2 + 0) * 32 + nl] = P0 * P1; AGG[(wid * 2 + 1) * 32 + nl] = fmaf(P1, E0, E1); }
;             LDS_BARRIER();
;             float cin = carry, cend = carry;
; #pragma unroll
	v_mov_b64_e32 v[112:113], v[64:65]
	v_mov_b64_e32 v[116:117], v[64:65]
	v_mov_b64_e32 v[120:121], v[64:65]
	v_mov_b64_e32 v[124:125], v[64:65]
	s_mov_b32 s46, 0
	s_mov_b32 s29, 0
	v_lshrrev_b32_e32 v32, 8, v167
	v_mul_u32_u24_e32 v33, 0x3600, v32
	v_add_u32_e32 v168, v168, v33
	v_add_u32_e32 v169, v169, v33
	v_add_u32_e32 v170, v170, v33
	v_add_u32_e32 v171, v171, v33
	v_add_u32_e32 v169, 0xffffee00, v169
	v_add_u32_e32 v170, 0xffffdc00, v170
	v_add_u32_e32 v171, 0xffffca00, v171
	v_mul_u32_u24_e32 v66, 0x60000, v32
	v_mov_b32_e32 v67, 0
	v_lshl_add_u64 v[142:143], v[66:67], 0, v[142:143]
	v_lshl_add_u64 v[252:253], v[66:67], 0, v[252:253]
	v_lshl_add_u64 v[154:155], v[66:67], 0, v[154:155]
	v_lshl_add_u64 v[150:151], v[66:67], 0, v[150:151]
	s_mov_b32 s19, -1
	s_mov_b32 s18, 0xfffe0000
	v_lshl_add_u64 v[252:253], v[252:253], 0, s[18:19]
	s_mov_b32 s18, 0xfffc0000
	v_lshl_add_u64 v[154:155], v[154:155], 0, s[18:19]
	s_mov_b32 s18, 0xfffa0000
	v_lshl_add_u64 v[150:151], v[150:151], 0, s[18:19]
	v_mul_u32_u24_e32 v33, 0x1400, v32
	v_add_u32_e32 v164, v164, v33
	v_add_u32_e32 v152, v152, v33
	v_add_u32_e32 v152, 0xffffec00, v152
	v_lshlrev_b32_e32 v33, 6, v32
	v_add_u32_e32 v140, v140, v33
	v_add_u32_e32 v138, v138, v33
	v_add_u32_e32 v138, 0xffffffc0, v138
	v_lshrrev_b32_e32 v33, 6, v167
	s_nop 1
	v_readfirstlane_b32 s18, v33
	s_lshl_b32 s19, s18, 6
	s_sub_i32 s19, s19, 0xe0
	s_mul_i32 s20, s19, 0x110
	v_add_u32_e32 v172, s20, v172
	v_add_u32_e32 v174, s20, v174
	v_add_u32_e32 v176, s20, v176
	v_add_u32_e32 v178, s20, v178
	v_add_u32_e32 v180, s20, v180
	v_add_u32_e32 v182, s20, v182
	v_add_u32_e32 v184, s20, v184
	v_add_u32_e32 v186, s20, v186
	v_add_u32_e32 v188, s20, v188
	v_add_u32_e32 v190, s20, v190
	v_add_u32_e32 v192, s20, v192
	v_add_u32_e32 v194, s20, v194
	v_add_u32_e32 v196, s20, v196
	v_add_u32_e32 v198, s20, v198
	v_add_u32_e32 v200, s20, v200
	v_add_u32_e32 v202, s20, v202
	v_add_u32_e32 v204, s20, v204
	s_mul_i32 s20, s19, 0x90
	v_add_u32_e32 v175, s20, v175
	v_add_u32_e32 v177, s20, v177
	v_add_u32_e32 v179, s20, v179
	v_add_u32_e32 v181, s20, v181
	v_add_u32_e32 v183, s20, v183
	v_add_u32_e32 v185, s20, v185
	v_add_u32_e32 v187, s20, v187
	v_add_u32_e32 v189, s20, v189
	v_add_u32_e32 v191, s20, v191
	v_add_u32_e32 v193, s20, v193
	v_add_u32_e32 v195, s20, v195
	v_add_u32_e32 v197, s20, v197
	v_add_u32_e32 v199, s20, v199
	v_add_u32_e32 v201, s20, v201
	v_add_u32_e32 v203, s20, v203
	v_add_u32_e32 v205, s20, v205
	s_mul_i32 s20, s19, 0x50
	v_add_u32_e32 v206, s20, v206
	v_add_u32_e32 v207, s20, v207
	v_add_u32_e32 v208, s20, v208
	v_add_u32_e32 v209, s20, v209
	v_add_u32_e32 v210, s20, v210
	v_add_u32_e32 v211, s20, v211
	v_add_u32_e32 v212, s20, v212
	v_add_u32_e32 v213, s20, v213
	v_add_u32_e32 v214, s20, v214
	v_add_u32_e32 v215, s20, v215
	v_add_u32_e32 v216, s20, v216
	v_add_u32_e32 v217, s20, v217
	v_add_u32_e32 v218, s20, v218
	v_add_u32_e32 v219, s20, v219
	v_add_u32_e32 v220, s20, v220
	v_add_u32_e32 v221, s20, v221
	s_lshl_b32 s20, s18, 1
	s_sub_i32 s20, 7, s20
	s_lshl_b32 s20, s20, 8
	v_add_u32_e32 v254, s20, v254
	s_sub_i32 s18, 7, s18
	s_lshr_b32 s101, s18, 2
	s_or_b32 s19, s18, 4
	s_cmp_eq_u32 s19, 7
	s_cselect_b64 s[0:1], -1, 0
	s_cmp_eq_u32 s19, 6
	s_cselect_b64 s[16:17], -1, 0
	s_cmp_eq_u32 s19, 5
	s_cselect_b64 s[4:5], -1, 0
	s_cmp_eq_u32 s19, 4
	s_cselect_b64 s[8:9], -1, 0
	s_cmp_eq_u32 s19, 3
	s_cselect_b64 s[10:11], -1, 0
	s_cmp_eq_u32 s19, 2
	s_cselect_b64 s[12:13], -1, 0
	s_cmp_eq_u32 s19, 1
	s_cselect_b64 s[14:15], -1, 0
	s_mov_b32 s98, 0
	s_cmp_eq_u32 s101, 0
	s_cselect_b32 s99, 0x14400, 0
	s_cselect_b32 s100, 0, 0x400
	v_add_u32_e32 v33, 0x14000, v254
	v_mov_b32_e32 v66, 1.0
	v_mov_b32_e32 v67, 0
	ds_write2_b32 v33, v66, v67 offset1:32
	s_cmp_eq_u32 s101, 0
	s_cbranch_scc1 .Lpp_b_nox
	s_waitcnt lgkmcnt(0)
	s_barrier

; #define LAS __attribute__((address_space(3)))
; template <int dir>
; __device__ __forceinline__ void lru_pass(LAS unsigned char* lds, const Params& P, int b, int h, int q, bool dry) {
;     ...
;                 } else if (!dry) {
; #pragma unroll
;                     for (int i = 0; i < 2; ++i) { const int id = tid + i * NTHREADS; *(u32x4*)(Z + ZSLAB(8 + h, (size_t)b * SEQ + t0_prev + (id >> 2)) + q * 32 + (id & 3) * 8) = *(const LAS u32x4*)(TOUT + (id >> 2) * IO_NP + (id & 3) * 16); }
;                 }
.LBB0_309:
	s_waitcnt lgkmcnt(0)
	s_barrier
	s_setprio 0
	s_cmp_lt_u32 s46, 2
	s_cbranch_scc1 .LBB0_311
	s_ashr_i32 s7, s78, 31
	s_add_u32 s6, s26, s78
	s_addc_u32 s7, s27, s7
	v_add_u32_e32 v32, v158, v164
	ds_read_b128 v[32:35], v32
	v_lshl_add_u64 v[36:37], s[6:7], 0, v[140:141]
	v_lshlrev_b64 v[36:37], 8, v[36:37]
	v_lshl_add_u64 v[40:41], v[136:137], 0, v[36:37]
	v_add_u32_e32 v36, v158, v152
	ds_read_b128 v[36:39], v36
	s_waitcnt lgkmcnt(1)
	global_store_dwordx4 v[40:41], v[32:35], off nt
	s_nop 1
	v_lshl_add_u64 v[32:33], s[6:7], 0, v[138:139]
	v_lshlrev_b64 v[32:33], 8, v[32:33]
	v_lshl_add_u64 v[32:33], v[136:137], 0, v[32:33]
	s_waitcnt lgkmcnt(0)
	global_store_dwordx4 v[32:33], v[36:39], off nt
